# v32 plus hand rewrite of the adaLN GEMV K loop: silu(c_sample) bf16 fragments hoisted out of the item loop, weight rows streamed 6 groups ahead
# baseline (speedup 1.0000x reference)
.LBB0_14:
	s_or_b64 exec, exec, s[6:7]
	s_lshr_b32 s3, s33, 6
	s_cmpk_lt_i32 s2, 0x300
	s_cselect_b64 s[6:7], -1, 0
	v_writelane_b32 v253, s3, 15
	v_writelane_b32 v254, s6, 42
	s_cmpk_gt_i32 s2, 0x2ff
	v_mbcnt_lo_u32_b32 v1, -1, 0
	v_writelane_b32 v254, s7, 43
	s_waitcnt lgkmcnt(0)
	s_barrier
	s_cbranch_scc1 .LBB0_24
	v_mbcnt_hi_u32_b32 v6, -1, v1
	v_and_b32_e32 v8, 64, v6
	v_xor_b32_e32 v7, 32, v6
	v_add_u32_e32 v8, 64, v8
	v_cmp_lt_i32_e32 vcc, v7, v8
	v_and_b32_e32 v2, 31, v4
	v_readlane_b32 s17, v253, 15
	v_cndmask_b32_e32 v6, v6, v7, vcc
	v_ashrrev_i32_e32 v3, 5, v4
	v_mov_b32_e32 v85, 0
	v_lshlrev_b32_e32 v84, 13, v2
	v_lshlrev_b32_e32 v83, 2, v6
	v_and_b32_e32 v6, 31, v82
	s_mul_i32 s16, s17, 0x1080
	s_add_i32 s3, 0, 0x12000
	v_lshlrev_b32_e32 v5, 3, v3
	v_lshl_add_u64 v[86:87], s[10:11], 0, v[84:85]
	v_lshlrev_b32_e32 v7, 2, v2
	v_lshlrev_b32_e32 v3, 9, v3
	v_lshlrev_b32_e32 v84, 2, v6
	s_add_i32 s6, s3, s16
	v_add3_u32 v3, s3, v7, v3
	v_add_u32_e32 v97, s3, v84
	s_lshl_b32 s3, s17, 10
	v_cmp_gt_u32_e32 vcc, 32, v4
	v_lshl_add_u32 v96, v4, 2, s6
	v_and_b32_e32 v4, 0xffffffe0, v4
	s_add_i32 s3, s3, 0
	s_movk_i32 s6, 0x420
	v_lshl_add_u64 v[8:9], s[4:5], 0, v[84:85]
	s_mov_b64 s[8:9], 0x100000
	v_add_u32_e32 v4, s3, v4
	v_cmp_gt_i32_e64 s[6:7], s6, v82
	v_lshl_add_u64 v[88:89], v[8:9], 0, s[8:9]
	v_add_u32_e32 v98, 0x10000, v4
	v_lshl_add_u32 v99, s17, 8, v5
	v_lshlrev_b32_e32 v90, 2, v2
	v_mov_b32_e32 v91, v85
	s_mov_b32 s3, 0xc000
	s_movk_i32 s20, 0x7fff
	s_mov_b32 s21, 0xffff0000
	v_add_u32_e32 v100, s16, v3
	v_lshlrev_b32_e32 v84, 2, v6
	s_movk_i32 s22, 0x21f
	s_mov_b32 s23, s2
	v_mov_b32_e32 v18, v99
	v_mov_b32_e32 v19, 0
	v_lshl_add_u64 v[20:21], v[18:19], 2, v[86:87]
	global_load_dwordx4 v[104:107], v[20:21], off offset:0
	global_load_dwordx4 v[108:111], v[20:21], off offset:16
	global_load_dwordx4 v[112:115], v[20:21], off offset:64
	global_load_dwordx4 v[116:119], v[20:21], off offset:80
	global_load_dwordx4 v[120:123], v[20:21], off offset:128
	global_load_dwordx4 v[124:127], v[20:21], off offset:144
	global_load_dwordx4 v[128:131], v[20:21], off offset:192
	global_load_dwordx4 v[132:135], v[20:21], off offset:208
	global_load_dwordx4 v[136:139], v[20:21], off offset:256
	global_load_dwordx4 v[140:143], v[20:21], off offset:272
	global_load_dwordx4 v[144:147], v[20:21], off offset:320
	global_load_dwordx4 v[148:151], v[20:21], off offset:336
	global_load_dwordx4 v[152:155], v[20:21], off offset:384
	global_load_dwordx4 v[156:159], v[20:21], off offset:400
	global_load_dwordx4 v[160:163], v[20:21], off offset:448
	global_load_dwordx4 v[164:167], v[20:21], off offset:464
	s_waitcnt vmcnt(14)
	v_mul_f32_e32 v24, 0xbfb8aa3b, v104
	v_mul_f32_e32 v25, 0xbfb8aa3b, v105
	v_mul_f32_e32 v26, 0xbfb8aa3b, v106
	v_mul_f32_e32 v27, 0xbfb8aa3b, v107
	v_mul_f32_e32 v28, 0xbfb8aa3b, v108
	v_mul_f32_e32 v29, 0xbfb8aa3b, v109
	v_mul_f32_e32 v30, 0xbfb8aa3b, v110
	v_mul_f32_e32 v31, 0xbfb8aa3b, v111
	v_exp_f32_e32 v24, v24
	v_exp_f32_e32 v25, v25
	v_exp_f32_e32 v26, v26
	v_exp_f32_e32 v27, v27
	v_exp_f32_e32 v28, v28
	v_exp_f32_e32 v29, v29
	v_exp_f32_e32 v30, v30
	v_exp_f32_e32 v31, v31
	v_add_f32_e32 v24, 1.0, v24
	v_add_f32_e32 v25, 1.0, v25
	v_add_f32_e32 v26, 1.0, v26
	v_add_f32_e32 v27, 1.0, v27
	v_add_f32_e32 v28, 1.0, v28
	v_add_f32_e32 v29, 1.0, v29
	v_add_f32_e32 v30, 1.0, v30
	v_add_f32_e32 v31, 1.0, v31
	v_rcp_f32_e32 v24, v24
	v_rcp_f32_e32 v25, v25
	v_rcp_f32_e32 v26, v26
	v_rcp_f32_e32 v27, v27
	v_rcp_f32_e32 v28, v28
	v_rcp_f32_e32 v29, v29
	v_rcp_f32_e32 v30, v30
	v_rcp_f32_e32 v31, v31
	v_mul_f32_e32 v104, v104, v24
	v_mul_f32_e32 v105, v105, v25
	v_mul_f32_e32 v106, v106, v26
	v_mul_f32_e32 v107, v107, v27
	v_mul_f32_e32 v108, v108, v28
	v_mul_f32_e32 v109, v109, v29
	v_mul_f32_e32 v110, v110, v30
	v_mul_f32_e32 v111, v111, v31
	v_cvt_pk_bf16_f32 v180, v104, v105
	v_cvt_pk_bf16_f32 v181, v106, v107
	v_cvt_pk_bf16_f32 v182, v108, v109
	v_cvt_pk_bf16_f32 v183, v110, v111
	s_waitcnt vmcnt(12)
	v_mul_f32_e32 v24, 0xbfb8aa3b, v112
	v_mul_f32_e32 v25, 0xbfb8aa3b, v113
	v_mul_f32_e32 v26, 0xbfb8aa3b, v114
	v_mul_f32_e32 v27, 0xbfb8aa3b, v115
	v_mul_f32_e32 v28, 0xbfb8aa3b, v116
	v_mul_f32_e32 v29, 0xbfb8aa3b, v117
	v_mul_f32_e32 v30, 0xbfb8aa3b, v118
	v_mul_f32_e32 v31, 0xbfb8aa3b, v119
	v_exp_f32_e32 v24, v24
	v_exp_f32_e32 v25, v25
	v_exp_f32_e32 v26, v26
	v_exp_f32_e32 v27, v27
	v_exp_f32_e32 v28, v28
	v_exp_f32_e32 v29, v29
	v_exp_f32_e32 v30, v30
	v_exp_f32_e32 v31, v31
	v_add_f32_e32 v24, 1.0, v24
	v_add_f32_e32 v25, 1.0, v25
	v_add_f32_e32 v26, 1.0, v26
	v_add_f32_e32 v27, 1.0, v27
	v_add_f32_e32 v28, 1.0, v28
	v_add_f32_e32 v29, 1.0, v29
	v_add_f32_e32 v30, 1.0, v30
	v_add_f32_e32 v31, 1.0, v31
	v_rcp_f32_e32 v24, v24
	v_rcp_f32_e32 v25, v25
	v_rcp_f32_e32 v26, v26
	v_rcp_f32_e32 v27, v27
	v_rcp_f32_e32 v28, v28
	v_rcp_f32_e32 v29, v29
	v_rcp_f32_e32 v30, v30
	v_rcp_f32_e32 v31, v31
	v_mul_f32_e32 v112, v112, v24
	v_mul_f32_e32 v113, v113, v25
	v_mul_f32_e32 v114, v114, v26
	v_mul_f32_e32 v115, v115, v27
	v_mul_f32_e32 v116, v116, v28
	v_mul_f32_e32 v117, v117, v29
	v_mul_f32_e32 v118, v118, v30
	v_mul_f32_e32 v119, v119, v31
	v_cvt_pk_bf16_f32 v184, v112, v113
	v_cvt_pk_bf16_f32 v185, v114, v115
	v_cvt_pk_bf16_f32 v186, v116, v117
	v_cvt_pk_bf16_f32 v187, v118, v119
	s_waitcnt vmcnt(10)
	v_mul_f32_e32 v24, 0xbfb8aa3b, v120
	v_mul_f32_e32 v25, 0xbfb8aa3b, v121
	v_mul_f32_e32 v26, 0xbfb8aa3b, v122
	v_mul_f32_e32 v27, 0xbfb8aa3b, v123
	v_mul_f32_e32 v28, 0xbfb8aa3b, v124
	v_mul_f32_e32 v29, 0xbfb8aa3b, v125
	v_mul_f32_e32 v30, 0xbfb8aa3b, v126
	v_mul_f32_e32 v31, 0xbfb8aa3b, v127
	v_exp_f32_e32 v24, v24
	v_exp_f32_e32 v25, v25
	v_exp_f32_e32 v26, v26
	v_exp_f32_e32 v27, v27
	v_exp_f32_e32 v28, v28
	v_exp_f32_e32 v29, v29
	v_exp_f32_e32 v30, v30
	v_exp_f32_e32 v31, v31
	v_add_f32_e32 v24, 1.0, v24
	v_add_f32_e32 v25, 1.0, v25
	v_add_f32_e32 v26, 1.0, v26
	v_add_f32_e32 v27, 1.0, v27
	v_add_f32_e32 v28, 1.0, v28
	v_add_f32_e32 v29, 1.0, v29
	v_add_f32_e32 v30, 1.0, v30
	v_add_f32_e32 v31, 1.0, v31
	v_rcp_f32_e32 v24, v24
	v_rcp_f32_e32 v25, v25
	v_rcp_f32_e32 v26, v26
	v_rcp_f32_e32 v27, v27
	v_rcp_f32_e32 v28, v28
	v_rcp_f32_e32 v29, v29
	v_rcp_f32_e32 v30, v30
	v_rcp_f32_e32 v31, v31
	v_mul_f32_e32 v120, v120, v24
	v_mul_f32_e32 v121, v121, v25
	v_mul_f32_e32 v122, v122, v26
	v_mul_f32_e32 v123, v123, v27
	v_mul_f32_e32 v124, v124, v28
	v_mul_f32_e32 v125, v125, v29
	v_mul_f32_e32 v126, v126, v30
	v_mul_f32_e32 v127, v127, v31
	v_cvt_pk_bf16_f32 v188, v120, v121
	v_cvt_pk_bf16_f32 v189, v122, v123
	v_cvt_pk_bf16_f32 v190, v124, v125
	v_cvt_pk_bf16_f32 v191, v126, v127
	s_waitcnt vmcnt(8)
	v_mul_f32_e32 v24, 0xbfb8aa3b, v128
	v_mul_f32_e32 v25, 0xbfb8aa3b, v129
	v_mul_f32_e32 v26, 0xbfb8aa3b, v130
	v_mul_f32_e32 v27, 0xbfb8aa3b, v131
	v_mul_f32_e32 v28, 0xbfb8aa3b, v132
	v_mul_f32_e32 v29, 0xbfb8aa3b, v133
	v_mul_f32_e32 v30, 0xbfb8aa3b, v134
	v_mul_f32_e32 v31, 0xbfb8aa3b, v135
	v_exp_f32_e32 v24, v24
	v_exp_f32_e32 v25, v25
	v_exp_f32_e32 v26, v26
	v_exp_f32_e32 v27, v27
	v_exp_f32_e32 v28, v28
	v_exp_f32_e32 v29, v29
	v_exp_f32_e32 v30, v30
	v_exp_f32_e32 v31, v31
	v_add_f32_e32 v24, 1.0, v24
	v_add_f32_e32 v25, 1.0, v25
	v_add_f32_e32 v26, 1.0, v26
	v_add_f32_e32 v27, 1.0, v27
	v_add_f32_e32 v28, 1.0, v28
	v_add_f32_e32 v29, 1.0, v29
	v_add_f32_e32 v30, 1.0, v30
	v_add_f32_e32 v31, 1.0, v31
	v_rcp_f32_e32 v24, v24
	v_rcp_f32_e32 v25, v25
	v_rcp_f32_e32 v26, v26
	v_rcp_f32_e32 v27, v27
	v_rcp_f32_e32 v28, v28
	v_rcp_f32_e32 v29, v29
	v_rcp_f32_e32 v30, v30
	v_rcp_f32_e32 v31, v31
	v_mul_f32_e32 v128, v128, v24
	v_mul_f32_e32 v129, v129, v25
	v_mul_f32_e32 v130, v130, v26
	v_mul_f32_e32 v131, v131, v27
	v_mul_f32_e32 v132, v132, v28
	v_mul_f32_e32 v133, v133, v29
	v_mul_f32_e32 v134, v134, v30
	v_mul_f32_e32 v135, v135, v31
	v_cvt_pk_bf16_f32 v192, v128, v129
	v_cvt_pk_bf16_f32 v193, v130, v131
	v_cvt_pk_bf16_f32 v194, v132, v133
	v_cvt_pk_bf16_f32 v195, v134, v135
	s_waitcnt vmcnt(6)
	v_mul_f32_e32 v24, 0xbfb8aa3b, v136
	v_mul_f32_e32 v25, 0xbfb8aa3b, v137
	v_mul_f32_e32 v26, 0xbfb8aa3b, v138
	v_mul_f32_e32 v27, 0xbfb8aa3b, v139
	v_mul_f32_e32 v28, 0xbfb8aa3b, v140
	v_mul_f32_e32 v29, 0xbfb8aa3b, v141
	v_mul_f32_e32 v30, 0xbfb8aa3b, v142
	v_mul_f32_e32 v31, 0xbfb8aa3b, v143
	v_exp_f32_e32 v24, v24
	v_exp_f32_e32 v25, v25
	v_exp_f32_e32 v26, v26
	v_exp_f32_e32 v27, v27
	v_exp_f32_e32 v28, v28
	v_exp_f32_e32 v29, v29
	v_exp_f32_e32 v30, v30
	v_exp_f32_e32 v31, v31
	v_add_f32_e32 v24, 1.0, v24
	v_add_f32_e32 v25, 1.0, v25
	v_add_f32_e32 v26, 1.0, v26
	v_add_f32_e32 v27, 1.0, v27
	v_add_f32_e32 v28, 1.0, v28
	v_add_f32_e32 v29, 1.0, v29
	v_add_f32_e32 v30, 1.0, v30
	v_add_f32_e32 v31, 1.0, v31
	v_rcp_f32_e32 v24, v24
	v_rcp_f32_e32 v25, v25
	v_rcp_f32_e32 v26, v26
	v_rcp_f32_e32 v27, v27
	v_rcp_f32_e32 v28, v28
	v_rcp_f32_e32 v29, v29
	v_rcp_f32_e32 v30, v30
	v_rcp_f32_e32 v31, v31
	v_mul_f32_e32 v136, v136, v24
	v_mul_f32_e32 v137, v137, v25
	v_mul_f32_e32 v138, v138, v26
	v_mul_f32_e32 v139, v139, v27
	v_mul_f32_e32 v140, v140, v28
	v_mul_f32_e32 v141, v141, v29
	v_mul_f32_e32 v142, v142, v30
	v_mul_f32_e32 v143, v143, v31
	v_cvt_pk_bf16_f32 v196, v136, v137
	v_cvt_pk_bf16_f32 v197, v138, v139
	v_cvt_pk_bf16_f32 v198, v140, v141
	v_cvt_pk_bf16_f32 v199, v142, v143
	s_waitcnt vmcnt(4)
	v_mul_f32_e32 v24, 0xbfb8aa3b, v144
	v_mul_f32_e32 v25, 0xbfb8aa3b, v145
	v_mul_f32_e32 v26, 0xbfb8aa3b, v146
	v_mul_f32_e32 v27, 0xbfb8aa3b, v147
	v_mul_f32_e32 v28, 0xbfb8aa3b, v148
	v_mul_f32_e32 v29, 0xbfb8aa3b, v149
	v_mul_f32_e32 v30, 0xbfb8aa3b, v150
	v_mul_f32_e32 v31, 0xbfb8aa3b, v151
	v_exp_f32_e32 v24, v24
	v_exp_f32_e32 v25, v25
	v_exp_f32_e32 v26, v26
	v_exp_f32_e32 v27, v27
	v_exp_f32_e32 v28, v28
	v_exp_f32_e32 v29, v29
	v_exp_f32_e32 v30, v30
	v_exp_f32_e32 v31, v31
	v_add_f32_e32 v24, 1.0, v24
	v_add_f32_e32 v25, 1.0, v25
	v_add_f32_e32 v26, 1.0, v26
	v_add_f32_e32 v27, 1.0, v27
	v_add_f32_e32 v28, 1.0, v28
	v_add_f32_e32 v29, 1.0, v29
	v_add_f32_e32 v30, 1.0, v30
	v_add_f32_e32 v31, 1.0, v31
	v_rcp_f32_e32 v24, v24
	v_rcp_f32_e32 v25, v25
	v_rcp_f32_e32 v26, v26
	v_rcp_f32_e32 v27, v27
	v_rcp_f32_e32 v28, v28
	v_rcp_f32_e32 v29, v29
	v_rcp_f32_e32 v30, v30
	v_rcp_f32_e32 v31, v31
	v_mul_f32_e32 v144, v144, v24
	v_mul_f32_e32 v145, v145, v25
	v_mul_f32_e32 v146, v146, v26
	v_mul_f32_e32 v147, v147, v27
	v_mul_f32_e32 v148, v148, v28
	v_mul_f32_e32 v149, v149, v29
	v_mul_f32_e32 v150, v150, v30
	v_mul_f32_e32 v151, v151, v31
	v_cvt_pk_bf16_f32 v200, v144, v145
	v_cvt_pk_bf16_f32 v201, v146, v147
	v_cvt_pk_bf16_f32 v202, v148, v149
	v_cvt_pk_bf16_f32 v203, v150, v151
	s_waitcnt vmcnt(2)
	v_mul_f32_e32 v24, 0xbfb8aa3b, v152
	v_mul_f32_e32 v25, 0xbfb8aa3b, v153
	v_mul_f32_e32 v26, 0xbfb8aa3b, v154
	v_mul_f32_e32 v27, 0xbfb8aa3b, v155
	v_mul_f32_e32 v28, 0xbfb8aa3b, v156
	v_mul_f32_e32 v29, 0xbfb8aa3b, v157
	v_mul_f32_e32 v30, 0xbfb8aa3b, v158
	v_mul_f32_e32 v31, 0xbfb8aa3b, v159
	v_exp_f32_e32 v24, v24
	v_exp_f32_e32 v25, v25
	v_exp_f32_e32 v26, v26
	v_exp_f32_e32 v27, v27
	v_exp_f32_e32 v28, v28
	v_exp_f32_e32 v29, v29
	v_exp_f32_e32 v30, v30
	v_exp_f32_e32 v31, v31
	v_add_f32_e32 v24, 1.0, v24
	v_add_f32_e32 v25, 1.0, v25
	v_add_f32_e32 v26, 1.0, v26
	v_add_f32_e32 v27, 1.0, v27
	v_add_f32_e32 v28, 1.0, v28
	v_add_f32_e32 v29, 1.0, v29
	v_add_f32_e32 v30, 1.0, v30
	v_add_f32_e32 v31, 1.0, v31
	v_rcp_f32_e32 v24, v24
	v_rcp_f32_e32 v25, v25
	v_rcp_f32_e32 v26, v26
	v_rcp_f32_e32 v27, v27
	v_rcp_f32_e32 v28, v28
	v_rcp_f32_e32 v29, v29
	v_rcp_f32_e32 v30, v30
	v_rcp_f32_e32 v31, v31
	v_mul_f32_e32 v152, v152, v24
	v_mul_f32_e32 v153, v153, v25
	v_mul_f32_e32 v154, v154, v26
	v_mul_f32_e32 v155, v155, v27
	v_mul_f32_e32 v156, v156, v28
	v_mul_f32_e32 v157, v157, v29
	v_mul_f32_e32 v158, v158, v30
	v_mul_f32_e32 v159, v159, v31
	v_cvt_pk_bf16_f32 v204, v152, v153
	v_cvt_pk_bf16_f32 v205, v154, v155
	v_cvt_pk_bf16_f32 v206, v156, v157
	v_cvt_pk_bf16_f32 v207, v158, v159
	s_waitcnt vmcnt(0)
	v_mul_f32_e32 v24, 0xbfb8aa3b, v160
	v_mul_f32_e32 v25, 0xbfb8aa3b, v161
	v_mul_f32_e32 v26, 0xbfb8aa3b, v162
	v_mul_f32_e32 v27, 0xbfb8aa3b, v163
	v_mul_f32_e32 v28, 0xbfb8aa3b, v164
	v_mul_f32_e32 v29, 0xbfb8aa3b, v165
	v_mul_f32_e32 v30, 0xbfb8aa3b, v166
	v_mul_f32_e32 v31, 0xbfb8aa3b, v167
	v_exp_f32_e32 v24, v24
	v_exp_f32_e32 v25, v25
	v_exp_f32_e32 v26, v26
	v_exp_f32_e32 v27, v27
	v_exp_f32_e32 v28, v28
	v_exp_f32_e32 v29, v29
	v_exp_f32_e32 v30, v30
	v_exp_f32_e32 v31, v31
	v_add_f32_e32 v24, 1.0, v24
	v_add_f32_e32 v25, 1.0, v25
	v_add_f32_e32 v26, 1.0, v26
	v_add_f32_e32 v27, 1.0, v27
	v_add_f32_e32 v28, 1.0, v28
	v_add_f32_e32 v29, 1.0, v29
	v_add_f32_e32 v30, 1.0, v30
	v_add_f32_e32 v31, 1.0, v31
	v_rcp_f32_e32 v24, v24
	v_rcp_f32_e32 v25, v25
	v_rcp_f32_e32 v26, v26
	v_rcp_f32_e32 v27, v27
	v_rcp_f32_e32 v28, v28
	v_rcp_f32_e32 v29, v29
	v_rcp_f32_e32 v30, v30
	v_rcp_f32_e32 v31, v31
	v_mul_f32_e32 v160, v160, v24
	v_mul_f32_e32 v161, v161, v25
	v_mul_f32_e32 v162, v162, v26
	v_mul_f32_e32 v163, v163, v27
	v_mul_f32_e32 v164, v164, v28
	v_mul_f32_e32 v165, v165, v29
	v_mul_f32_e32 v166, v166, v30
	v_mul_f32_e32 v167, v167, v31
	v_cvt_pk_bf16_f32 v208, v160, v161
	v_cvt_pk_bf16_f32 v209, v162, v163
	v_cvt_pk_bf16_f32 v210, v164, v165
	v_cvt_pk_bf16_f32 v211, v166, v167
	global_load_dwordx4 v[104:107], v[20:21], off offset:512
	global_load_dwordx4 v[108:111], v[20:21], off offset:528
	global_load_dwordx4 v[112:115], v[20:21], off offset:576
	global_load_dwordx4 v[116:119], v[20:21], off offset:592
	global_load_dwordx4 v[120:123], v[20:21], off offset:640
	global_load_dwordx4 v[124:127], v[20:21], off offset:656
	global_load_dwordx4 v[128:131], v[20:21], off offset:704
	global_load_dwordx4 v[132:135], v[20:21], off offset:720
	global_load_dwordx4 v[136:139], v[20:21], off offset:768
	global_load_dwordx4 v[140:143], v[20:21], off offset:784
	global_load_dwordx4 v[144:147], v[20:21], off offset:832
	global_load_dwordx4 v[148:151], v[20:21], off offset:848
	global_load_dwordx4 v[152:155], v[20:21], off offset:896
	global_load_dwordx4 v[156:159], v[20:21], off offset:912
	global_load_dwordx4 v[160:163], v[20:21], off offset:960
	global_load_dwordx4 v[164:167], v[20:21], off offset:976
	s_waitcnt vmcnt(14)
	v_mul_f32_e32 v24, 0xbfb8aa3b, v104
	v_mul_f32_e32 v25, 0xbfb8aa3b, v105
	v_mul_f32_e32 v26, 0xbfb8aa3b, v106
	v_mul_f32_e32 v27, 0xbfb8aa3b, v107
	v_mul_f32_e32 v28, 0xbfb8aa3b, v108
	v_mul_f32_e32 v29, 0xbfb8aa3b, v109
	v_mul_f32_e32 v30, 0xbfb8aa3b, v110
	v_mul_f32_e32 v31, 0xbfb8aa3b, v111
	v_exp_f32_e32 v24, v24
	v_exp_f32_e32 v25, v25
	v_exp_f32_e32 v26, v26
	v_exp_f32_e32 v27, v27
	v_exp_f32_e32 v28, v28
	v_exp_f32_e32 v29, v29
	v_exp_f32_e32 v30, v30
	v_exp_f32_e32 v31, v31
	v_add_f32_e32 v24, 1.0, v24
	v_add_f32_e32 v25, 1.0, v25
	v_add_f32_e32 v26, 1.0, v26
	v_add_f32_e32 v27, 1.0, v27
	v_add_f32_e32 v28, 1.0, v28
	v_add_f32_e32 v29, 1.0, v29
	v_add_f32_e32 v30, 1.0, v30
	v_add_f32_e32 v31, 1.0, v31
	v_rcp_f32_e32 v24, v24
	v_rcp_f32_e32 v25, v25
	v_rcp_f32_e32 v26, v26
	v_rcp_f32_e32 v27, v27
	v_rcp_f32_e32 v28, v28
	v_rcp_f32_e32 v29, v29
	v_rcp_f32_e32 v30, v30
	v_rcp_f32_e32 v31, v31
	v_mul_f32_e32 v104, v104, v24
	v_mul_f32_e32 v105, v105, v25
	v_mul_f32_e32 v106, v106, v26
	v_mul_f32_e32 v107, v107, v27
	v_mul_f32_e32 v108, v108, v28
	v_mul_f32_e32 v109, v109, v29
	v_mul_f32_e32 v110, v110, v30
	v_mul_f32_e32 v111, v111, v31
	v_cvt_pk_bf16_f32 v212, v104, v105
	v_cvt_pk_bf16_f32 v213, v106, v107
	v_cvt_pk_bf16_f32 v214, v108, v109
	v_cvt_pk_bf16_f32 v215, v110, v111
	s_waitcnt vmcnt(12)
	v_mul_f32_e32 v24, 0xbfb8aa3b, v112
	v_mul_f32_e32 v25, 0xbfb8aa3b, v113
	v_mul_f32_e32 v26, 0xbfb8aa3b, v114
	v_mul_f32_e32 v27, 0xbfb8aa3b, v115
	v_mul_f32_e32 v28, 0xbfb8aa3b, v116
	v_mul_f32_e32 v29, 0xbfb8aa3b, v117
	v_mul_f32_e32 v30, 0xbfb8aa3b, v118
	v_mul_f32_e32 v31, 0xbfb8aa3b, v119
	v_exp_f32_e32 v24, v24
	v_exp_f32_e32 v25, v25
	v_exp_f32_e32 v26, v26
	v_exp_f32_e32 v27, v27
	v_exp_f32_e32 v28, v28
	v_exp_f32_e32 v29, v29
	v_exp_f32_e32 v30, v30
	v_exp_f32_e32 v31, v31
	v_add_f32_e32 v24, 1.0, v24
	v_add_f32_e32 v25, 1.0, v25
	v_add_f32_e32 v26, 1.0, v26
	v_add_f32_e32 v27, 1.0, v27
	v_add_f32_e32 v28, 1.0, v28
	v_add_f32_e32 v29, 1.0, v29
	v_add_f32_e32 v30, 1.0, v30
	v_add_f32_e32 v31, 1.0, v31
	v_rcp_f32_e32 v24, v24
	v_rcp_f32_e32 v25, v25
	v_rcp_f32_e32 v26, v26
	v_rcp_f32_e32 v27, v27
	v_rcp_f32_e32 v28, v28
	v_rcp_f32_e32 v29, v29
	v_rcp_f32_e32 v30, v30
	v_rcp_f32_e32 v31, v31
	v_mul_f32_e32 v112, v112, v24
	v_mul_f32_e32 v113, v113, v25
	v_mul_f32_e32 v114, v114, v26
	v_mul_f32_e32 v115, v115, v27
	v_mul_f32_e32 v116, v116, v28
	v_mul_f32_e32 v117, v117, v29
	v_mul_f32_e32 v118, v118, v30
	v_mul_f32_e32 v119, v119, v31
	v_cvt_pk_bf16_f32 v216, v112, v113
	v_cvt_pk_bf16_f32 v217, v114, v115
	v_cvt_pk_bf16_f32 v218, v116, v117
	v_cvt_pk_bf16_f32 v219, v118, v119
	s_waitcnt vmcnt(10)
	v_mul_f32_e32 v24, 0xbfb8aa3b, v120
	v_mul_f32_e32 v25, 0xbfb8aa3b, v121
	v_mul_f32_e32 v26, 0xbfb8aa3b, v122
	v_mul_f32_e32 v27, 0xbfb8aa3b, v123
	v_mul_f32_e32 v28, 0xbfb8aa3b, v124
	v_mul_f32_e32 v29, 0xbfb8aa3b, v125
	v_mul_f32_e32 v30, 0xbfb8aa3b, v126
	v_mul_f32_e32 v31, 0xbfb8aa3b, v127
	v_exp_f32_e32 v24, v24
	v_exp_f32_e32 v25, v25
	v_exp_f32_e32 v26, v26
	v_exp_f32_e32 v27, v27
	v_exp_f32_e32 v28, v28
	v_exp_f32_e32 v29, v29
	v_exp_f32_e32 v30, v30
	v_exp_f32_e32 v31, v31
	v_add_f32_e32 v24, 1.0, v24
	v_add_f32_e32 v25, 1.0, v25
	v_add_f32_e32 v26, 1.0, v26
	v_add_f32_e32 v27, 1.0, v27
	v_add_f32_e32 v28, 1.0, v28
	v_add_f32_e32 v29, 1.0, v29
	v_add_f32_e32 v30, 1.0, v30
	v_add_f32_e32 v31, 1.0, v31
	v_rcp_f32_e32 v24, v24
	v_rcp_f32_e32 v25, v25
	v_rcp_f32_e32 v26, v26
	v_rcp_f32_e32 v27, v27
	v_rcp_f32_e32 v28, v28
	v_rcp_f32_e32 v29, v29
	v_rcp_f32_e32 v30, v30
	v_rcp_f32_e32 v31, v31
	v_mul_f32_e32 v120, v120, v24
	v_mul_f32_e32 v121, v121, v25
	v_mul_f32_e32 v122, v122, v26
	v_mul_f32_e32 v123, v123, v27
	v_mul_f32_e32 v124, v124, v28
	v_mul_f32_e32 v125, v125, v29
	v_mul_f32_e32 v126, v126, v30
	v_mul_f32_e32 v127, v127, v31
	v_cvt_pk_bf16_f32 v220, v120, v121
	v_cvt_pk_bf16_f32 v221, v122, v123
	v_cvt_pk_bf16_f32 v222, v124, v125
	v_cvt_pk_bf16_f32 v223, v126, v127
	s_waitcnt vmcnt(8)
	v_mul_f32_e32 v24, 0xbfb8aa3b, v128
	v_mul_f32_e32 v25, 0xbfb8aa3b, v129
	v_mul_f32_e32 v26, 0xbfb8aa3b, v130
	v_mul_f32_e32 v27, 0xbfb8aa3b, v131
	v_mul_f32_e32 v28, 0xbfb8aa3b, v132
	v_mul_f32_e32 v29, 0xbfb8aa3b, v133
	v_mul_f32_e32 v30, 0xbfb8aa3b, v134
	v_mul_f32_e32 v31, 0xbfb8aa3b, v135
	v_exp_f32_e32 v24, v24
	v_exp_f32_e32 v25, v25
	v_exp_f32_e32 v26, v26
	v_exp_f32_e32 v27, v27
	v_exp_f32_e32 v28, v28
	v_exp_f32_e32 v29, v29
	v_exp_f32_e32 v30, v30
	v_exp_f32_e32 v31, v31
	v_add_f32_e32 v24, 1.0, v24
	v_add_f32_e32 v25, 1.0, v25
	v_add_f32_e32 v26, 1.0, v26
	v_add_f32_e32 v27, 1.0, v27
	v_add_f32_e32 v28, 1.0, v28
	v_add_f32_e32 v29, 1.0, v29
	v_add_f32_e32 v30, 1.0, v30
	v_add_f32_e32 v31, 1.0, v31
	v_rcp_f32_e32 v24, v24
	v_rcp_f32_e32 v25, v25
	v_rcp_f32_e32 v26, v26
	v_rcp_f32_e32 v27, v27
	v_rcp_f32_e32 v28, v28
	v_rcp_f32_e32 v29, v29
	v_rcp_f32_e32 v30, v30
	v_rcp_f32_e32 v31, v31
	v_mul_f32_e32 v128, v128, v24
	v_mul_f32_e32 v129, v129, v25
	v_mul_f32_e32 v130, v130, v26
	v_mul_f32_e32 v131, v131, v27
	v_mul_f32_e32 v132, v132, v28
	v_mul_f32_e32 v133, v133, v29
	v_mul_f32_e32 v134, v134, v30
	v_mul_f32_e32 v135, v135, v31
	v_cvt_pk_bf16_f32 v224, v128, v129
	v_cvt_pk_bf16_f32 v225, v130, v131
	v_cvt_pk_bf16_f32 v226, v132, v133
	v_cvt_pk_bf16_f32 v227, v134, v135
	s_waitcnt vmcnt(6)
	v_mul_f32_e32 v24, 0xbfb8aa3b, v136
	v_mul_f32_e32 v25, 0xbfb8aa3b, v137
	v_mul_f32_e32 v26, 0xbfb8aa3b, v138
	v_mul_f32_e32 v27, 0xbfb8aa3b, v139
	v_mul_f32_e32 v28, 0xbfb8aa3b, v140
	v_mul_f32_e32 v29, 0xbfb8aa3b, v141
	v_mul_f32_e32 v30, 0xbfb8aa3b, v142
	v_mul_f32_e32 v31, 0xbfb8aa3b, v143
	v_exp_f32_e32 v24, v24
	v_exp_f32_e32 v25, v25
	v_exp_f32_e32 v26, v26
	v_exp_f32_e32 v27, v27
	v_exp_f32_e32 v28, v28
	v_exp_f32_e32 v29, v29
	v_exp_f32_e32 v30, v30
	v_exp_f32_e32 v31, v31
	v_add_f32_e32 v24, 1.0, v24
	v_add_f32_e32 v25, 1.0, v25
	v_add_f32_e32 v26, 1.0, v26
	v_add_f32_e32 v27, 1.0, v27
	v_add_f32_e32 v28, 1.0, v28
	v_add_f32_e32 v29, 1.0, v29
	v_add_f32_e32 v30, 1.0, v30
	v_add_f32_e32 v31, 1.0, v31
	v_rcp_f32_e32 v24, v24
	v_rcp_f32_e32 v25, v25
	v_rcp_f32_e32 v26, v26
	v_rcp_f32_e32 v27, v27
	v_rcp_f32_e32 v28, v28
	v_rcp_f32_e32 v29, v29
	v_rcp_f32_e32 v30, v30
	v_rcp_f32_e32 v31, v31
	v_mul_f32_e32 v136, v136, v24
	v_mul_f32_e32 v137, v137, v25
	v_mul_f32_e32 v138, v138, v26
	v_mul_f32_e32 v139, v139, v27
	v_mul_f32_e32 v140, v140, v28
	v_mul_f32_e32 v141, v141, v29
	v_mul_f32_e32 v142, v142, v30
	v_mul_f32_e32 v143, v143, v31
	v_cvt_pk_bf16_f32 v228, v136, v137
	v_cvt_pk_bf16_f32 v229, v138, v139
	v_cvt_pk_bf16_f32 v230, v140, v141
	v_cvt_pk_bf16_f32 v231, v142, v143
	s_waitcnt vmcnt(4)
	v_mul_f32_e32 v24, 0xbfb8aa3b, v144
	v_mul_f32_e32 v25, 0xbfb8aa3b, v145
	v_mul_f32_e32 v26, 0xbfb8aa3b, v146
	v_mul_f32_e32 v27, 0xbfb8aa3b, v147
	v_mul_f32_e32 v28, 0xbfb8aa3b, v148
	v_mul_f32_e32 v29, 0xbfb8aa3b, v149
	v_mul_f32_e32 v30, 0xbfb8aa3b, v150
	v_mul_f32_e32 v31, 0xbfb8aa3b, v151
	v_exp_f32_e32 v24, v24
	v_exp_f32_e32 v25, v25
	v_exp_f32_e32 v26, v26
	v_exp_f32_e32 v27, v27
	v_exp_f32_e32 v28, v28
	v_exp_f32_e32 v29, v29
	v_exp_f32_e32 v30, v30
	v_exp_f32_e32 v31, v31
	v_add_f32_e32 v24, 1.0, v24
	v_add_f32_e32 v25, 1.0, v25
	v_add_f32_e32 v26, 1.0, v26
	v_add_f32_e32 v27, 1.0, v27
	v_add_f32_e32 v28, 1.0, v28
	v_add_f32_e32 v29, 1.0, v29
	v_add_f32_e32 v30, 1.0, v30
	v_add_f32_e32 v31, 1.0, v31
	v_rcp_f32_e32 v24, v24
	v_rcp_f32_e32 v25, v25
	v_rcp_f32_e32 v26, v26
	v_rcp_f32_e32 v27, v27
	v_rcp_f32_e32 v28, v28
	v_rcp_f32_e32 v29, v29
	v_rcp_f32_e32 v30, v30
	v_rcp_f32_e32 v31, v31
	v_mul_f32_e32 v144, v144, v24
	v_mul_f32_e32 v145, v145, v25
	v_mul_f32_e32 v146, v146, v26
	v_mul_f32_e32 v147, v147, v27
	v_mul_f32_e32 v148, v148, v28
	v_mul_f32_e32 v149, v149, v29
	v_mul_f32_e32 v150, v150, v30
	v_mul_f32_e32 v151, v151, v31
	v_cvt_pk_bf16_f32 v236, v144, v145
	v_cvt_pk_bf16_f32 v237, v146, v147
	v_cvt_pk_bf16_f32 v238, v148, v149
	v_cvt_pk_bf16_f32 v239, v150, v151
	s_waitcnt vmcnt(2)
	v_mul_f32_e32 v24, 0xbfb8aa3b, v152
	v_mul_f32_e32 v25, 0xbfb8aa3b, v153
	v_mul_f32_e32 v26, 0xbfb8aa3b, v154
	v_mul_f32_e32 v27, 0xbfb8aa3b, v155
	v_mul_f32_e32 v28, 0xbfb8aa3b, v156
	v_mul_f32_e32 v29, 0xbfb8aa3b, v157
	v_mul_f32_e32 v30, 0xbfb8aa3b, v158
	v_mul_f32_e32 v31, 0xbfb8aa3b, v159
	v_exp_f32_e32 v24, v24
	v_exp_f32_e32 v25, v25
	v_exp_f32_e32 v26, v26
	v_exp_f32_e32 v27, v27
	v_exp_f32_e32 v28, v28
	v_exp_f32_e32 v29, v29
	v_exp_f32_e32 v30, v30
	v_exp_f32_e32 v31, v31
	v_add_f32_e32 v24, 1.0, v24
	v_add_f32_e32 v25, 1.0, v25
	v_add_f32_e32 v26, 1.0, v26
	v_add_f32_e32 v27, 1.0, v27
	v_add_f32_e32 v28, 1.0, v28
	v_add_f32_e32 v29, 1.0, v29
	v_add_f32_e32 v30, 1.0, v30
	v_add_f32_e32 v31, 1.0, v31
	v_rcp_f32_e32 v24, v24
	v_rcp_f32_e32 v25, v25
	v_rcp_f32_e32 v26, v26
	v_rcp_f32_e32 v27, v27
	v_rcp_f32_e32 v28, v28
	v_rcp_f32_e32 v29, v29
	v_rcp_f32_e32 v30, v30
	v_rcp_f32_e32 v31, v31
	v_mul_f32_e32 v152, v152, v24
	v_mul_f32_e32 v153, v153, v25
	v_mul_f32_e32 v154, v154, v26
	v_mul_f32_e32 v155, v155, v27
	v_mul_f32_e32 v156, v156, v28
	v_mul_f32_e32 v157, v157, v29
	v_mul_f32_e32 v158, v158, v30
	v_mul_f32_e32 v159, v159, v31
	v_cvt_pk_bf16_f32 v240, v152, v153
	v_cvt_pk_bf16_f32 v241, v154, v155
	v_cvt_pk_bf16_f32 v242, v156, v157
	v_cvt_pk_bf16_f32 v243, v158, v159
	s_waitcnt vmcnt(0)
	v_mul_f32_e32 v24, 0xbfb8aa3b, v160
	v_mul_f32_e32 v25, 0xbfb8aa3b, v161
	v_mul_f32_e32 v26, 0xbfb8aa3b, v162
	v_mul_f32_e32 v27, 0xbfb8aa3b, v163
	v_mul_f32_e32 v28, 0xbfb8aa3b, v164
	v_mul_f32_e32 v29, 0xbfb8aa3b, v165
	v_mul_f32_e32 v30, 0xbfb8aa3b, v166
	v_mul_f32_e32 v31, 0xbfb8aa3b, v167
	v_exp_f32_e32 v24, v24
	v_exp_f32_e32 v25, v25
	v_exp_f32_e32 v26, v26
	v_exp_f32_e32 v27, v27
	v_exp_f32_e32 v28, v28
	v_exp_f32_e32 v29, v29
	v_exp_f32_e32 v30, v30
	v_exp_f32_e32 v31, v31
	v_add_f32_e32 v24, 1.0, v24
	v_add_f32_e32 v25, 1.0, v25
	v_add_f32_e32 v26, 1.0, v26
	v_add_f32_e32 v27, 1.0, v27
	v_add_f32_e32 v28, 1.0, v28
	v_add_f32_e32 v29, 1.0, v29
	v_add_f32_e32 v30, 1.0, v30
	v_add_f32_e32 v31, 1.0, v31
	v_rcp_f32_e32 v24, v24
	v_rcp_f32_e32 v25, v25
	v_rcp_f32_e32 v26, v26
	v_rcp_f32_e32 v27, v27
	v_rcp_f32_e32 v28, v28
	v_rcp_f32_e32 v29, v29
	v_rcp_f32_e32 v30, v30
	v_rcp_f32_e32 v31, v31
	v_mul_f32_e32 v160, v160, v24
	v_mul_f32_e32 v161, v161, v25
	v_mul_f32_e32 v162, v162, v26
	v_mul_f32_e32 v163, v163, v27
	v_mul_f32_e32 v164, v164, v28
	v_mul_f32_e32 v165, v165, v29
	v_mul_f32_e32 v166, v166, v30
	v_mul_f32_e32 v167, v167, v31
	v_cvt_pk_bf16_f32 v244, v160, v161
	v_cvt_pk_bf16_f32 v245, v162, v163
	v_cvt_pk_bf16_f32 v246, v164, v165
	v_cvt_pk_bf16_f32 v247, v166, v167
	s_branch .LBB0_17

.LBB0_17:
	s_mul_hi_i32 s8, s23, 0x2aaaaaab
	s_lshr_b32 s9, s8, 31
	s_ashr_i32 s8, s8, 6
	s_add_i32 s18, s8, s9
	s_mul_i32 s8, s18, 0x180
	s_sub_i32 s8, s23, s8
	s_lshl_b32 s8, s8, 5
	s_mul_i32 s10, s18, 0x6000000
	s_mul_hi_i32 s9, s18, 0x6000000
	s_add_u32 s10, s12, s10
	s_addc_u32 s11, s13, s9
	s_ashr_i32 s9, s8, 31
	s_lshl_b64 s[8:9], s[8:9], 2
	s_add_u32 s10, s10, s8
	s_addc_u32 s11, s11, s9
	v_lshl_add_u64 v[92:93], s[10:11], 0, v[90:91]
	v_mov_b32_e32 v102, v98
	s_mov_b64 s[24:25], s[10:11]
	v_mov_b32_e32 v101, 0
	v_mov_b32_e32 v2, 0
	v_mov_b32_e32 v3, v85
	v_mov_b32_e32 v4, v85
	v_mov_b32_e32 v5, v85
	v_mov_b32_e32 v6, v85
	v_mov_b32_e32 v7, v85
	v_mov_b32_e32 v8, v85
	v_mov_b32_e32 v9, v85
	v_mov_b32_e32 v10, v85
	v_mov_b32_e32 v11, v85
	v_mov_b32_e32 v12, v85
	v_mov_b32_e32 v13, v85
	v_mov_b32_e32 v14, v85
	v_mov_b32_e32 v15, v85
	v_mov_b32_e32 v16, v85
	v_mov_b32_e32 v17, v85
	v_mad_u32_u24 v44, v99, s3, v90
	v_add_u32_e32 v45, s3, v44
	v_add_u32_e32 v46, s3, v45
	v_add_u32_e32 v47, s3, v46
	v_add_u32_e32 v48, s3, v47
	v_add_u32_e32 v49, s3, v48
	v_add_u32_e32 v50, s3, v49
	v_add_u32_e32 v51, s3, v50
	global_load_dword v104, v44, s[24:25]
	global_load_dword v105, v45, s[24:25]
	global_load_dword v106, v46, s[24:25]
	global_load_dword v107, v47, s[24:25]
	global_load_dword v108, v48, s[24:25]
	global_load_dword v109, v49, s[24:25]
	global_load_dword v110, v50, s[24:25]
	global_load_dword v111, v51, s[24:25]
	s_add_u32 s24, s24, 0xc0000
	s_addc_u32 s25, s25, 0
	global_load_dword v112, v44, s[24:25]
	global_load_dword v113, v45, s[24:25]
	global_load_dword v114, v46, s[24:25]
	global_load_dword v115, v47, s[24:25]
	global_load_dword v116, v48, s[24:25]
	global_load_dword v117, v49, s[24:25]
	global_load_dword v118, v50, s[24:25]
	global_load_dword v119, v51, s[24:25]
	s_add_u32 s24, s24, 0xc0000
	s_addc_u32 s25, s25, 0
	global_load_dword v120, v44, s[24:25]
	global_load_dword v121, v45, s[24:25]
	global_load_dword v122, v46, s[24:25]
	global_load_dword v123, v47, s[24:25]
	global_load_dword v124, v48, s[24:25]
	global_load_dword v125, v49, s[24:25]
	global_load_dword v126, v50, s[24:25]
	global_load_dword v127, v51, s[24:25]
	s_add_u32 s24, s24, 0xc0000
	s_addc_u32 s25, s25, 0
	global_load_dword v128, v44, s[24:25]
	global_load_dword v129, v45, s[24:25]
	global_load_dword v130, v46, s[24:25]
	global_load_dword v131, v47, s[24:25]
	global_load_dword v132, v48, s[24:25]
	global_load_dword v133, v49, s[24:25]
	global_load_dword v134, v50, s[24:25]
	global_load_dword v135, v51, s[24:25]
	s_add_u32 s24, s24, 0xc0000
	s_addc_u32 s25, s25, 0
	global_load_dword v136, v44, s[24:25]
	global_load_dword v137, v45, s[24:25]
	global_load_dword v138, v46, s[24:25]
	global_load_dword v139, v47, s[24:25]
	global_load_dword v140, v48, s[24:25]
	global_load_dword v141, v49, s[24:25]
	global_load_dword v142, v50, s[24:25]
	global_load_dword v143, v51, s[24:25]
	s_add_u32 s24, s24, 0xc0000
	s_addc_u32 s25, s25, 0
	global_load_dword v144, v44, s[24:25]
	global_load_dword v145, v45, s[24:25]
	global_load_dword v146, v46, s[24:25]
	global_load_dword v147, v47, s[24:25]
	global_load_dword v148, v48, s[24:25]
	global_load_dword v149, v49, s[24:25]
	global_load_dword v150, v50, s[24:25]
	global_load_dword v151, v51, s[24:25]
	s_add_u32 s24, s24, 0xc0000
	s_addc_u32 s25, s25, 0
	ds_read_b128 v[28:31], v102 offset:0
	ds_read_b128 v[32:35], v102 offset:16
	global_load_dword v152, v44, s[24:25]
	global_load_dword v153, v45, s[24:25]
	global_load_dword v154, v46, s[24:25]
	global_load_dword v155, v47, s[24:25]
	global_load_dword v156, v48, s[24:25]
	global_load_dword v157, v49, s[24:25]
	global_load_dword v158, v50, s[24:25]
	global_load_dword v159, v51, s[24:25]
	s_add_u32 s24, s24, 0xc0000
	s_addc_u32 s25, s25, 0
	ds_read_b128 v[36:39], v102 offset:64
	ds_read_b128 v[40:43], v102 offset:80
	s_waitcnt vmcnt(48)
	v_cvt_pk_bf16_f32 v20, v104, v105
	v_cvt_pk_bf16_f32 v21, v106, v107
	v_cvt_pk_bf16_f32 v22, v108, v109
	v_cvt_pk_bf16_f32 v23, v110, v111
	s_waitcnt lgkmcnt(2)
	v_fmac_f32_e32 v101, v28, v104
	v_fmac_f32_e32 v101, v29, v105
	v_fmac_f32_e32 v101, v30, v106
	v_fmac_f32_e32 v101, v31, v107
	v_fmac_f32_e32 v101, v32, v108
	v_fmac_f32_e32 v101, v33, v109
	v_fmac_f32_e32 v101, v34, v110
	v_fmac_f32_e32 v101, v35, v111
	v_mfma_f32_32x32x16_bf16 v[2:17], v[180:183], v[20:23], v[2:17]
	global_load_dword v160, v44, s[24:25]
	global_load_dword v161, v45, s[24:25]
	global_load_dword v162, v46, s[24:25]
	global_load_dword v163, v47, s[24:25]
	global_load_dword v164, v48, s[24:25]
	global_load_dword v165, v49, s[24:25]
	global_load_dword v166, v50, s[24:25]
	global_load_dword v167, v51, s[24:25]
	s_add_u32 s24, s24, 0xc0000
	s_addc_u32 s25, s25, 0
	ds_read_b128 v[28:31], v102 offset:128
	ds_read_b128 v[32:35], v102 offset:144
	s_waitcnt vmcnt(48)
	v_cvt_pk_bf16_f32 v24, v112, v113
	v_cvt_pk_bf16_f32 v25, v114, v115
	v_cvt_pk_bf16_f32 v26, v116, v117
	v_cvt_pk_bf16_f32 v27, v118, v119
	s_waitcnt lgkmcnt(2)
	v_fmac_f32_e32 v101, v36, v112
	v_fmac_f32_e32 v101, v37, v113
	v_fmac_f32_e32 v101, v38, v114
	v_fmac_f32_e32 v101, v39, v115
	v_fmac_f32_e32 v101, v40, v116
	v_fmac_f32_e32 v101, v41, v117
	v_fmac_f32_e32 v101, v42, v118
	v_fmac_f32_e32 v101, v43, v119
	v_mfma_f32_32x32x16_bf16 v[2:17], v[184:187], v[24:27], v[2:17]
	global_load_dword v104, v44, s[24:25]
	global_load_dword v105, v45, s[24:25]
	global_load_dword v106, v46, s[24:25]
	global_load_dword v107, v47, s[24:25]
	global_load_dword v108, v48, s[24:25]
	global_load_dword v109, v49, s[24:25]
	global_load_dword v110, v50, s[24:25]
	global_load_dword v111, v51, s[24:25]
	s_add_u32 s24, s24, 0xc0000
	s_addc_u32 s25, s25, 0
	ds_read_b128 v[36:39], v102 offset:192
	ds_read_b128 v[40:43], v102 offset:208
	s_waitcnt vmcnt(48)
	v_cvt_pk_bf16_f32 v20, v120, v121
	v_cvt_pk_bf16_f32 v21, v122, v123
	v_cvt_pk_bf16_f32 v22, v124, v125
	v_cvt_pk_bf16_f32 v23, v126, v127
	s_waitcnt lgkmcnt(2)
	v_fmac_f32_e32 v101, v28, v120
	v_fmac_f32_e32 v101, v29, v121
	v_fmac_f32_e32 v101, v30, v122
	v_fmac_f32_e32 v101, v31, v123
	v_fmac_f32_e32 v101, v32, v124
	v_fmac_f32_e32 v101, v33, v125
	v_fmac_f32_e32 v101, v34, v126
	v_fmac_f32_e32 v101, v35, v127
	v_mfma_f32_32x32x16_bf16 v[2:17], v[188:191], v[20:23], v[2:17]
	global_load_dword v112, v44, s[24:25]
	global_load_dword v113, v45, s[24:25]
	global_load_dword v114, v46, s[24:25]
	global_load_dword v115, v47, s[24:25]
	global_load_dword v116, v48, s[24:25]
	global_load_dword v117, v49, s[24:25]
	global_load_dword v118, v50, s[24:25]
	global_load_dword v119, v51, s[24:25]
	s_add_u32 s24, s24, 0xc0000
	s_addc_u32 s25, s25, 0
	ds_read_b128 v[28:31], v102 offset:256
	ds_read_b128 v[32:35], v102 offset:272
	s_waitcnt vmcnt(48)
	v_cvt_pk_bf16_f32 v24, v128, v129
	v_cvt_pk_bf16_f32 v25, v130, v131
	v_cvt_pk_bf16_f32 v26, v132, v133
	v_cvt_pk_bf16_f32 v27, v134, v135
	s_waitcnt lgkmcnt(2)
	v_fmac_f32_e32 v101, v36, v128
	v_fmac_f32_e32 v101, v37, v129
	v_fmac_f32_e32 v101, v38, v130
	v_fmac_f32_e32 v101, v39, v131
	v_fmac_f32_e32 v101, v40, v132
	v_fmac_f32_e32 v101, v41, v133
	v_fmac_f32_e32 v101, v42, v134
	v_fmac_f32_e32 v101, v43, v135
	v_mfma_f32_32x32x16_bf16 v[2:17], v[192:195], v[24:27], v[2:17]
	global_load_dword v120, v44, s[24:25]
	global_load_dword v121, v45, s[24:25]
	global_load_dword v122, v46, s[24:25]
	global_load_dword v123, v47, s[24:25]
	global_load_dword v124, v48, s[24:25]
	global_load_dword v125, v49, s[24:25]
	global_load_dword v126, v50, s[24:25]
	global_load_dword v127, v51, s[24:25]
	s_add_u32 s24, s24, 0xc0000
	s_addc_u32 s25, s25, 0
	ds_read_b128 v[36:39], v102 offset:320
	ds_read_b128 v[40:43], v102 offset:336
	s_waitcnt vmcnt(48)
	v_cvt_pk_bf16_f32 v20, v136, v137
	v_cvt_pk_bf16_f32 v21, v138, v139
	v_cvt_pk_bf16_f32 v22, v140, v141
	v_cvt_pk_bf16_f32 v23, v142, v143
	s_waitcnt lgkmcnt(2)
	v_fmac_f32_e32 v101, v28, v136
	v_fmac_f32_e32 v101, v29, v137
	v_fmac_f32_e32 v101, v30, v138
	v_fmac_f32_e32 v101, v31, v139
	v_fmac_f32_e32 v101, v32, v140
	v_fmac_f32_e32 v101, v33, v141
	v_fmac_f32_e32 v101, v34, v142
	v_fmac_f32_e32 v101, v35, v143
	v_mfma_f32_32x32x16_bf16 v[2:17], v[196:199], v[20:23], v[2:17]
	global_load_dword v128, v44, s[24:25]
	global_load_dword v129, v45, s[24:25]
	global_load_dword v130, v46, s[24:25]
	global_load_dword v131, v47, s[24:25]
	global_load_dword v132, v48, s[24:25]
	global_load_dword v133, v49, s[24:25]
	global_load_dword v134, v50, s[24:25]
	global_load_dword v135, v51, s[24:25]
	s_add_u32 s24, s24, 0xc0000
	s_addc_u32 s25, s25, 0
	ds_read_b128 v[28:31], v102 offset:384
	ds_read_b128 v[32:35], v102 offset:400
	s_waitcnt vmcnt(48)
	v_cvt_pk_bf16_f32 v24, v144, v145
	v_cvt_pk_bf16_f32 v25, v146, v147
	v_cvt_pk_bf16_f32 v26, v148, v149
	v_cvt_pk_bf16_f32 v27, v150, v151
	s_waitcnt lgkmcnt(2)
	v_fmac_f32_e32 v101, v36, v144
	v_fmac_f32_e32 v101, v37, v145
	v_fmac_f32_e32 v101, v38, v146
	v_fmac_f32_e32 v101, v39, v147
	v_fmac_f32_e32 v101, v40, v148
	v_fmac_f32_e32 v101, v41, v149
	v_fmac_f32_e32 v101, v42, v150
	v_fmac_f32_e32 v101, v43, v151
	v_mfma_f32_32x32x16_bf16 v[2:17], v[200:203], v[24:27], v[2:17]
	global_load_dword v136, v44, s[24:25]
	global_load_dword v137, v45, s[24:25]
	global_load_dword v138, v46, s[24:25]
	global_load_dword v139, v47, s[24:25]
	global_load_dword v140, v48, s[24:25]
	global_load_dword v141, v49, s[24:25]
	global_load_dword v142, v50, s[24:25]
	global_load_dword v143, v51, s[24:25]
	s_add_u32 s24, s24, 0xc0000
	s_addc_u32 s25, s25, 0
	ds_read_b128 v[36:39], v102 offset:448
	ds_read_b128 v[40:43], v102 offset:464
	s_waitcnt vmcnt(48)
	v_cvt_pk_bf16_f32 v20, v152, v153
	v_cvt_pk_bf16_f32 v21, v154, v155
	v_cvt_pk_bf16_f32 v22, v156, v157
	v_cvt_pk_bf16_f32 v23, v158, v159
	s_waitcnt lgkmcnt(2)
	v_fmac_f32_e32 v101, v28, v152
	v_fmac_f32_e32 v101, v29, v153
	v_fmac_f32_e32 v101, v30, v154
	v_fmac_f32_e32 v101, v31, v155
	v_fmac_f32_e32 v101, v32, v156
	v_fmac_f32_e32 v101, v33, v157
	v_fmac_f32_e32 v101, v34, v158
	v_fmac_f32_e32 v101, v35, v159
	v_mfma_f32_32x32x16_bf16 v[2:17], v[204:207], v[20:23], v[2:17]
	global_load_dword v144, v44, s[24:25]
	global_load_dword v145, v45, s[24:25]
	global_load_dword v146, v46, s[24:25]
	global_load_dword v147, v47, s[24:25]
	global_load_dword v148, v48, s[24:25]
	global_load_dword v149, v49, s[24:25]
	global_load_dword v150, v50, s[24:25]
	global_load_dword v151, v51, s[24:25]
	s_add_u32 s24, s24, 0xc0000
	s_addc_u32 s25, s25, 0
	ds_read_b128 v[28:31], v102 offset:512
	ds_read_b128 v[32:35], v102 offset:528
	s_waitcnt vmcnt(48)
	v_cvt_pk_bf16_f32 v24, v160, v161
	v_cvt_pk_bf16_f32 v25, v162, v163
	v_cvt_pk_bf16_f32 v26, v164, v165
	v_cvt_pk_bf16_f32 v27, v166, v167
	s_waitcnt lgkmcnt(2)
	v_fmac_f32_e32 v101, v36, v160
	v_fmac_f32_e32 v101, v37, v161
	v_fmac_f32_e32 v101, v38, v162
	v_fmac_f32_e32 v101, v39, v163
	v_fmac_f32_e32 v101, v40, v164
	v_fmac_f32_e32 v101, v41, v165
	v_fmac_f32_e32 v101, v42, v166
	v_fmac_f32_e32 v101, v43, v167
	v_mfma_f32_32x32x16_bf16 v[2:17], v[208:211], v[24:27], v[2:17]
	global_load_dword v152, v44, s[24:25]
	global_load_dword v153, v45, s[24:25]
	global_load_dword v154, v46, s[24:25]
	global_load_dword v155, v47, s[24:25]
	global_load_dword v156, v48, s[24:25]
	global_load_dword v157, v49, s[24:25]
	global_load_dword v158, v50, s[24:25]
	global_load_dword v159, v51, s[24:25]
	s_add_u32 s24, s24, 0xc0000
	s_addc_u32 s25, s25, 0
	ds_read_b128 v[36:39], v102 offset:576
	ds_read_b128 v[40:43], v102 offset:592
	s_waitcnt vmcnt(48)
	v_cvt_pk_bf16_f32 v20, v104, v105
	v_cvt_pk_bf16_f32 v21, v106, v107
	v_cvt_pk_bf16_f32 v22, v108, v109
	v_cvt_pk_bf16_f32 v23, v110, v111
	s_waitcnt lgkmcnt(2)
	v_fmac_f32_e32 v101, v28, v104
	v_fmac_f32_e32 v101, v29, v105
	v_fmac_f32_e32 v101, v30, v106
	v_fmac_f32_e32 v101, v31, v107
	v_fmac_f32_e32 v101, v32, v108
	v_fmac_f32_e32 v101, v33, v109
	v_fmac_f32_e32 v101, v34, v110
	v_fmac_f32_e32 v101, v35, v111
	v_mfma_f32_32x32x16_bf16 v[2:17], v[212:215], v[20:23], v[2:17]
	global_load_dword v160, v44, s[24:25]
	global_load_dword v161, v45, s[24:25]
	global_load_dword v162, v46, s[24:25]
	global_load_dword v163, v47, s[24:25]
	global_load_dword v164, v48, s[24:25]
	global_load_dword v165, v49, s[24:25]
	global_load_dword v166, v50, s[24:25]
	global_load_dword v167, v51, s[24:25]
	s_add_u32 s24, s24, 0xc0000
	s_addc_u32 s25, s25, 0
	ds_read_b128 v[28:31], v102 offset:640
	ds_read_b128 v[32:35], v102 offset:656
	s_waitcnt vmcnt(48)
	v_cvt_pk_bf16_f32 v24, v112, v113
	v_cvt_pk_bf16_f32 v25, v114, v115
	v_cvt_pk_bf16_f32 v26, v116, v117
	v_cvt_pk_bf16_f32 v27, v118, v119
	s_waitcnt lgkmcnt(2)
	v_fmac_f32_e32 v101, v36, v112
	v_fmac_f32_e32 v101, v37, v113
	v_fmac_f32_e32 v101, v38, v114
	v_fmac_f32_e32 v101, v39, v115
	v_fmac_f32_e32 v101, v40, v116
	v_fmac_f32_e32 v101, v41, v117
	v_fmac_f32_e32 v101, v42, v118
	v_fmac_f32_e32 v101, v43, v119
	v_mfma_f32_32x32x16_bf16 v[2:17], v[216:219], v[24:27], v[2:17]
	ds_read_b128 v[36:39], v102 offset:704
	ds_read_b128 v[40:43], v102 offset:720
	s_waitcnt vmcnt(40)
	v_cvt_pk_bf16_f32 v20, v120, v121
	v_cvt_pk_bf16_f32 v21, v122, v123
	v_cvt_pk_bf16_f32 v22, v124, v125
	v_cvt_pk_bf16_f32 v23, v126, v127
	s_waitcnt lgkmcnt(2)
	v_fmac_f32_e32 v101, v28, v120
	v_fmac_f32_e32 v101, v29, v121
	v_fmac_f32_e32 v101, v30, v122
	v_fmac_f32_e32 v101, v31, v123
	v_fmac_f32_e32 v101, v32, v124
	v_fmac_f32_e32 v101, v33, v125
	v_fmac_f32_e32 v101, v34, v126
	v_fmac_f32_e32 v101, v35, v127
	v_mfma_f32_32x32x16_bf16 v[2:17], v[220:223], v[20:23], v[2:17]
	ds_read_b128 v[28:31], v102 offset:768
	ds_read_b128 v[32:35], v102 offset:784
	s_waitcnt vmcnt(32)
	v_cvt_pk_bf16_f32 v24, v128, v129
	v_cvt_pk_bf16_f32 v25, v130, v131
	v_cvt_pk_bf16_f32 v26, v132, v133
	v_cvt_pk_bf16_f32 v27, v134, v135
	s_waitcnt lgkmcnt(2)
	v_fmac_f32_e32 v101, v36, v128
	v_fmac_f32_e32 v101, v37, v129
	v_fmac_f32_e32 v101, v38, v130
	v_fmac_f32_e32 v101, v39, v131
	v_fmac_f32_e32 v101, v40, v132
	v_fmac_f32_e32 v101, v41, v133
	v_fmac_f32_e32 v101, v42, v134
	v_fmac_f32_e32 v101, v43, v135
	v_mfma_f32_32x32x16_bf16 v[2:17], v[224:227], v[24:27], v[2:17]
	ds_read_b128 v[36:39], v102 offset:832
	ds_read_b128 v[40:43], v102 offset:848
	s_waitcnt vmcnt(24)
	v_cvt_pk_bf16_f32 v20, v136, v137
	v_cvt_pk_bf16_f32 v21, v138, v139
	v_cvt_pk_bf16_f32 v22, v140, v141
	v_cvt_pk_bf16_f32 v23, v142, v143
	s_waitcnt lgkmcnt(2)
	v_fmac_f32_e32 v101, v28, v136
	v_fmac_f32_e32 v101, v29, v137
	v_fmac_f32_e32 v101, v30, v138
	v_fmac_f32_e32 v101, v31, v139
	v_fmac_f32_e32 v101, v32, v140
	v_fmac_f32_e32 v101, v33, v141
	v_fmac_f32_e32 v101, v34, v142
	v_fmac_f32_e32 v101, v35, v143
	v_mfma_f32_32x32x16_bf16 v[2:17], v[228:231], v[20:23], v[2:17]
	ds_read_b128 v[28:31], v102 offset:896
	ds_read_b128 v[32:35], v102 offset:912
	s_waitcnt vmcnt(16)
	v_cvt_pk_bf16_f32 v24, v144, v145
	v_cvt_pk_bf16_f32 v25, v146, v147
	v_cvt_pk_bf16_f32 v26, v148, v149
	v_cvt_pk_bf16_f32 v27, v150, v151
	s_waitcnt lgkmcnt(2)
	v_fmac_f32_e32 v101, v36, v144
	v_fmac_f32_e32 v101, v37, v145
	v_fmac_f32_e32 v101, v38, v146
	v_fmac_f32_e32 v101, v39, v147
	v_fmac_f32_e32 v101, v40, v148
	v_fmac_f32_e32 v101, v41, v149
	v_fmac_f32_e32 v101, v42, v150
	v_fmac_f32_e32 v101, v43, v151
	v_mfma_f32_32x32x16_bf16 v[2:17], v[236:239], v[24:27], v[2:17]
	ds_read_b128 v[36:39], v102 offset:960
	ds_read_b128 v[40:43], v102 offset:976
	s_waitcnt vmcnt(8)
	v_cvt_pk_bf16_f32 v20, v152, v153
	v_cvt_pk_bf16_f32 v21, v154, v155
	v_cvt_pk_bf16_f32 v22, v156, v157
	v_cvt_pk_bf16_f32 v23, v158, v159
	s_waitcnt lgkmcnt(2)
	v_fmac_f32_e32 v101, v28, v152
	v_fmac_f32_e32 v101, v29, v153
	v_fmac_f32_e32 v101, v30, v154
	v_fmac_f32_e32 v101, v31, v155
	v_fmac_f32_e32 v101, v32, v156
	v_fmac_f32_e32 v101, v33, v157
	v_fmac_f32_e32 v101, v34, v158
	v_fmac_f32_e32 v101, v35, v159
	v_mfma_f32_32x32x16_bf16 v[2:17], v[240:243], v[20:23], v[2:17]
	s_waitcnt vmcnt(0)
	v_cvt_pk_bf16_f32 v24, v160, v161
	v_cvt_pk_bf16_f32 v25, v162, v163
	v_cvt_pk_bf16_f32 v26, v164, v165
	v_cvt_pk_bf16_f32 v27, v166, v167
	s_waitcnt lgkmcnt(0)
	v_fmac_f32_e32 v101, v36, v160
	v_fmac_f32_e32 v101, v37, v161
	v_fmac_f32_e32 v101, v38, v162
	v_fmac_f32_e32 v101, v39, v163
	v_fmac_f32_e32 v101, v40, v164
	v_fmac_f32_e32 v101, v41, v165
	v_fmac_f32_e32 v101, v42, v166
	v_fmac_f32_e32 v101, v43, v167
	v_mfma_f32_32x32x16_bf16 v[2:17], v[244:247], v[24:27], v[2:17]
	s_nop 7
	s_nop 4
	ds_bpermute_b32 v18, v83, v101
	s_nop 0
	ds_write2_b32 v100, v2, v3 offset0:32 offset1:64
	ds_write2_b32 v100, v4, v5 offset0:96 offset1:128
	v_add_u32_e32 v2, 0x400, v100
	ds_write2_b32 v2, v6, v7 offset0:32 offset1:64
	ds_write2_b32 v2, v8, v9 offset0:96 offset1:128
	v_add_u32_e32 v2, 0x800, v100
	ds_write2_b32 v2, v10, v11 offset0:32 offset1:64
	ds_write2_b32 v2, v12, v13 offset0:96 offset1:128
	v_add_u32_e32 v2, 0xc00, v100
	ds_write2_b32 v2, v14, v15 offset0:32 offset1:64
	ds_write2_b32 v2, v16, v17 offset0:96 offset1:128
	s_and_saveexec_b64 s[10:11], vcc
	s_cbranch_execz .LBB0_21
	s_waitcnt lgkmcnt(8)
	v_add_f32_e32 v2, v101, v18
	ds_write_b32 v96, v2
